# P3 rebalance: bit5 blocks do all pooling items first, other blocks do all sample mLSTM items
# speedup vs baseline: 1.0097x; 1.0097x over previous
; #define OPAQUE_TID() int tid = threadIdx.x; asm volatile("" : "+v"(tid)); const int lane = tid & 63, wave = __builtin_amdgcn_readfirstlane(tid >> 6); (void)lane; (void)wave
; __device__ __forceinline__ void pool_prepass(const Args& a) {
;     OPAQUE_TID();
;     const bf16_t* U = (const bf16_t*)(a.ws + WS_U);
;     bf16_t* PB = (bf16_t*)a.out;
;     const int G = gridDim.x, gq = wave & 3, ch = gq * 256 + (lane & 31) * 8;
;     for (int it = blockIdx.x; it < MT / 64; it += G) {
;         const int row0 = (it * 4 + (wave >> 2) * 2 + (lane >> 5)) * 16;
;         if (gq == 0) pool_run<2>(a, U, PB, row0, ch);
;         else if (gq == 1) pool_run<4>(a, U, PB, row0, ch);
;         else if (gq == 2) pool_run<8>(a, U, PB, row0, ch);
;         else pool_run<16>(a, U, PB, row0, ch);
;     }
; __global__ void __launch_bounds__(512, 2) fwd_megakernel(Args a) {
;     ...
;         if ((bid >> 5) & 1) pool_prepass(a);
.LBB0_341:
	s_or_b64 exec, exec, s[0:1]
	s_bitcmp0_b32 s2, 5
	s_cselect_b64 s[40:41], -1, 0
	s_and_b64 vcc, exec, s[40:41]
	s_waitcnt lgkmcnt(0)
	s_barrier
	s_cbranch_vccnz .LBB0_642
	s_and_b32 s98, s2, 31
	s_lshr_b32 s99, s2, 6
	s_lshl_b32 s99, s99, 5
	s_or_b32 s98, s98, s99
	s_movk_i32 s99, 0x80
	v_mov_b32_e32 v0, v180
	s_cmpk_gt_i32 s98, 0x20f
	v_readfirstlane_b32 s0, v0
	s_cbranch_scc1 .LBB0_642
	v_lshlrev_b32_e32 v1, 3, v0
	s_bfe_u32 s12, s0, 0x20006
	v_and_b32_e32 v1, 0xf8, v1
	s_ashr_i32 s0, s0, 7
	v_lshl_or_b32 v124, s12, 8, v1
	s_and_b32 s0, s0, -2
	s_lshl_b32 s1, s98, 2
	v_bfe_u32 v125, v0, 5, 1
	v_mov_b32_e32 v127, 0
	v_lshlrev_b32_e32 v126, 1, v124
	s_add_i32 s13, s1, s0
	v_lshl_add_u64 v[128:129], s[28:29], 0, v[126:127]
	v_lshl_add_u64 v[130:131], s[26:27], 0, v[126:127]
	v_lshlrev_b32_e32 v126, 2, v124
	v_or_b32_e32 v0, s13, v125
	v_lshl_add_u64 v[132:133], s[44:45], 0, v[126:127]
	s_lshl_b32 s14, s99, 2
	v_lshl_or_b32 v134, v0, 4, 15
	s_lshl_b32 s15, s99, 6
	s_movk_i32 s42, 0x7ff
	v_mov_b32_e32 v139, 0xfffff80f
	v_not_b32_e32 v170, 16
	v_mov_b32_e32 v171, 0x7ff
	s_movk_i32 s43, 0x3800
	s_mov_b32 s52, 0x3d800000
	s_mov_b32 s53, 0x3e000000
	s_mov_b32 s54, 0x3e800000
	v_mov_b32_e32 v172, 0x7f1
	v_mov_b32_e32 v173, 0x2100000
	v_mov_b32_e32 v174, 0x2540040
	v_mov_b32_e32 v175, 0x41800000
	v_mov_b32_e32 v176, 0x41000000
	s_mov_b32 s55, s98
	s_branch .LBB0_345
.LBB0_344:
	s_or_b64 exec, exec, s[0:1]
	s_add_i32 s55, s55, s99
	s_add_i32 s13, s13, s14
	s_cmpk_lt_i32 s55, 0x210
	v_add_u32_e32 v134, s15, v134
	s_cbranch_scc0 .LBB0_642

; #define LAS __attribute__((address_space(3)))
; #define OPAQUE_TID() int tid = threadIdx.x; asm volatile("" : "+v"(tid)); const int lane = tid & 63, wave = __builtin_amdgcn_readfirstlane(tid >> 6); (void)lane; (void)wave
; __device__ __forceinline__ void mlstm_item(const Args& a, LAS unsigned char* L, bool sample, int b, int hh, int sl, bool dry = false) {
;     OPAQUE_TID();
;     bf16_t* U = (bf16_t*)(a.ws + WS_U);
;     const float* gates = (const float*)(a.ws + WS_GATES);
;     const int g = lane >> 4, lr = lane & 15, t32 = lane & 31;
;     const int rowbase = sample ? MP + b * SSEQ : b * SEQ;
;     const int nchunks = sample ? 1 : SEQ / 32;
;     const float bi = a.in[12][hh], bfv = a.in[13][hh];
; __global__ void __launch_bounds__(512, 2) fwd_megakernel(Args a) {
;     ...
;         for (int it = bid; it < 512; it += G) { const int x = it & 7, loc = it >> 3, bh = x * 16 + (loc >> 2); mlstm_item(a, L, true, bh >> 2, bh & 3, loc & 3); }
.LBB0_707:
	s_bitcmp1_b32 s2, 5
	s_cbranch_scc1 .LBB0_775
	s_and_b32 s98, s2, 31
	s_lshr_b32 s99, s2, 6
	s_lshl_b32 s99, s99, 5
	s_or_b32 s98, s98, s99
	s_movk_i32 s99, 0x80
	s_add_u32 s33, s26, 0x96e0100
	s_addc_u32 s56, s27, 0
	s_add_u32 s57, s26, 0xb6e0100
	s_addc_u32 s58, s27, 0
	s_add_u32 s59, s26, 0xb700100
	s_addc_u32 s64, s27, 0
	s_lshl_b32 s65, s98, 4
	s_lshl_b32 s68, s99, 4
	s_mov_b32 s11, 0
	v_mov_b32_e32 v41, 0
	v_mov_b32_e32 v86, 0x3f80
	s_movk_i32 s69, 0x50
	s_movk_i32 s70, 0x210
	s_movk_i32 s71, 0x3800
	s_movk_i32 s72, 0x100
	s_movk_i32 s73, 0x3000
	s_mov_b32 s76, 0xbfb8aa3b
	s_mov_b32 s77, 0x3f2aaaab
	v_mov_b32_e32 v87, 0x3ecc95a3
	s_mov_b32 s78, 0x3f317218
	s_mov_b32 s79, 0x7f800000
	s_mov_b32 s80, 0x33800000
	v_mov_b32_e32 v88, 0xff800000
	s_add_i32 s81, 0, 0x1e700
	s_movk_i32 s82, 0xfe1f
	s_mov_b32 s83, 0xffff
	s_movk_i32 s84, 0x140
	s_movk_i32 s85, 0x20c
	s_mov_b32 s86, 0xc000
	s_movk_i32 s87, 0xfe40
	s_movk_i32 s88, 0x1c0
	v_mov_b32_e32 v89, 0x4200
	v_mov_b32_e32 v90, 0x6300
	v_mov_b32_e32 v91, 0x7f800000
	v_mov_b32_e32 v92, 0x7fc00000
	v_mbcnt_hi_u32_b32 v93, -1, v181
	s_mov_b32 s89, s98
	s_branch .LBB0_710
.LBB0_709:
	s_or_b64 exec, exec, s[0:1]
	s_waitcnt lgkmcnt(0)
	s_barrier
	s_add_i32 s89, s89, s99
	s_add_i32 s65, s65, s68
	s_cmpk_gt_i32 s89, 0x1ff
	s_cbranch_scc1 .LBB0_775

; #define OPAQUE_TID() int tid = threadIdx.x; asm volatile("" : "+v"(tid)); const int lane = tid & 63, wave = __builtin_amdgcn_readfirstlane(tid >> 6); (void)lane; (void)wave
; __device__ __forceinline__ void pool_prepass(const Args& a) {
;     OPAQUE_TID();
;     const bf16_t* U = (const bf16_t*)(a.ws + WS_U);
;     bf16_t* PB = (bf16_t*)a.out;
;     const int G = gridDim.x, gq = wave & 3, ch = gq * 256 + (lane & 31) * 8;
;     for (int it = blockIdx.x; it < MT / 64; it += G) {
;         const int row0 = (it * 4 + (wave >> 2) * 2 + (lane >> 5)) * 16;
;         if (gq == 0) pool_run<2>(a, U, PB, row0, ch);
;         else if (gq == 1) pool_run<4>(a, U, PB, row0, ch);
;         else if (gq == 2) pool_run<8>(a, U, PB, row0, ch);
;         else pool_run<16>(a, U, PB, row0, ch);
;     }
; __global__ void __launch_bounds__(512, 2) fwd_megakernel(Args a) {
;     ...
;         if (!((bid >> 5) & 1)) pool_prepass(a);
.LBB0_775:
	s_and_b64 vcc, exec, s[40:41]
	s_branch .LBB0_1076
	v_mov_b32_e32 v0, v180
	s_cmpk_gt_i32 s2, 0x20f
	v_readfirstlane_b32 s0, v0
	s_cbranch_scc1 .LBB0_1076
	v_lshlrev_b32_e32 v1, 3, v0
	s_bfe_u32 s12, s0, 0x20006
	v_and_b32_e32 v1, 0xf8, v1
	s_ashr_i32 s0, s0, 7
	v_lshl_or_b32 v124, s12, 8, v1
	s_and_b32 s0, s0, -2
	s_lshl_b32 s1, s2, 2
	v_bfe_u32 v125, v0, 5, 1
	v_mov_b32_e32 v127, 0
	v_lshlrev_b32_e32 v126, 1, v124
	s_add_i32 s13, s1, s0
	v_lshl_add_u64 v[128:129], s[28:29], 0, v[126:127]
	v_lshl_add_u64 v[130:131], s[26:27], 0, v[126:127]
	v_lshlrev_b32_e32 v126, 2, v124
	v_or_b32_e32 v0, s13, v125
	v_lshl_add_u64 v[132:133], s[44:45], 0, v[126:127]
	s_lshl_b32 s14, s30, 2
	v_lshl_or_b32 v134, v0, 4, 15
	s_lshl_b32 s15, s30, 6
	s_movk_i32 s40, 0x7ff
	v_mov_b32_e32 v139, 0xfffff80f
	v_not_b32_e32 v170, 16
	v_mov_b32_e32 v171, 0x7ff
	s_movk_i32 s41, 0x3800
	s_mov_b32 s42, 0x3d800000
	s_mov_b32 s43, 0x3e000000
	s_mov_b32 s44, 0x3e800000
	v_mov_b32_e32 v172, 0x7f1
	v_mov_b32_e32 v173, 0x2100000
	v_mov_b32_e32 v174, 0x2540040
	v_mov_b32_e32 v175, 0x41800000
	v_mov_b32_e32 v176, 0x41000000
	s_mov_b32 s45, s2
	s_branch .LBB0_779

; __global__ void __launch_bounds__(512, 2) fwd_megakernel(Args a) {
	.amdhsa_kernel _Z14fwd_megakernel4Args
		.amdhsa_group_segment_fixed_size 0
		.amdhsa_private_segment_fixed_size 0
		.amdhsa_kernarg_size 424
		.amdhsa_user_sgpr_count 2
		.amdhsa_user_sgpr_dispatch_ptr 0
		.amdhsa_user_sgpr_queue_ptr 0
		.amdhsa_user_sgpr_kernarg_segment_ptr 1
		.amdhsa_user_sgpr_dispatch_id 0
		.amdhsa_user_sgpr_kernarg_preload_length 0
		.amdhsa_user_sgpr_kernarg_preload_offset 0
		.amdhsa_user_sgpr_private_segment_size 0
		.amdhsa_uses_dynamic_stack 0
		.amdhsa_enable_private_segment 0
		.amdhsa_system_sgpr_workgroup_id_x 1
		.amdhsa_system_sgpr_workgroup_id_y 0
		.amdhsa_system_sgpr_workgroup_id_z 0
		.amdhsa_system_sgpr_workgroup_info 0
		.amdhsa_system_vgpr_workitem_id 2
		.amdhsa_next_free_vgpr 255
		.amdhsa_next_free_sgpr 100
		.amdhsa_accum_offset 256
		.amdhsa_reserve_vcc 1
		.amdhsa_float_round_mode_32 0
		.amdhsa_float_round_mode_16_64 0
		.amdhsa_float_denorm_mode_32 3
		.amdhsa_float_denorm_mode_16_64 3
		.amdhsa_dx10_clamp 1
		.amdhsa_ieee_mode 1
		.amdhsa_fp16_overflow 0
		.amdhsa_tg_split 0
		.amdhsa_exception_fp_ieee_invalid_op 0
		.amdhsa_exception_fp_denorm_src 0
		.amdhsa_exception_fp_ieee_div_zero 0
		.amdhsa_exception_fp_ieee_overflow 0
		.amdhsa_exception_fp_ieee_underflow 0
		.amdhsa_exception_fp_ieee_inexact 0
		.amdhsa_exception_int_div_zero 0
	.end_amdhsa_kernel

; __global__ void __launch_bounds__(512, 2) fwd_megakernel(Args a) {
amdhsa.kernels:
  - .agpr_count:     0
    .args:
      - .offset:         0
        .size:           168
        .value_kind:     by_value
      - .offset:         168
        .size:           4
        .value_kind:     hidden_block_count_x
      - .offset:         172
        .size:           4
        .value_kind:     hidden_block_count_y
      - .offset:         176
        .size:           4
        .value_kind:     hidden_block_count_z
      - .offset:         180
        .size:           2
        .value_kind:     hidden_group_size_x
      - .offset:         182
        .size:           2
        .value_kind:     hidden_group_size_y
      - .offset:         184
        .size:           2
        .value_kind:     hidden_group_size_z
      - .offset:         186
        .size:           2
        .value_kind:     hidden_remainder_x
      - .offset:         188
        .size:           2
        .value_kind:     hidden_remainder_y
      - .offset:         190
        .size:           2
        .value_kind:     hidden_remainder_z
      - .offset:         208
        .size:           8
        .value_kind:     hidden_global_offset_x
      - .offset:         216
        .size:           8
        .value_kind:     hidden_global_offset_y
      - .offset:         224
        .size:           8
        .value_kind:     hidden_global_offset_z
      - .offset:         232
        .size:           2
        .value_kind:     hidden_grid_dims
      - .offset:         256
        .size:           8
        .value_kind:     hidden_multigrid_sync_arg
      - .offset:         288
        .size:           4
        .value_kind:     hidden_dynamic_lds_size
    .group_segment_fixed_size: 0
    .kernarg_segment_align: 8
    .kernarg_segment_size: 424
    .language:       OpenCL C
    .language_version:
      - 2
      - 0
    .max_flat_workgroup_size: 512
    .name:           _Z14fwd_megakernel4Args
    .private_segment_fixed_size: 0
    .sgpr_count:     106
    .sgpr_spill_count: 4
    .symbol:         _Z14fwd_megakernel4Args.kd
    .uniform_work_group_size: 1
    .uses_dynamic_stack: false
    .vgpr_count:     255
    .vgpr_spill_count: 0
    .wavefront_size: 64
